# static priority raise for waves 4-7 in the GLA chunk loops (state pass and output pass)
# speedup vs baseline: 1.0079x; 1.0079x over previous
; template <int MODE>
; __device__ __forceinline__ void gla_item(const int TID, const Params& p, int l, int ci, int head, LAS unsigned char* lds, const float (&wg)[2][16], const float (&bg)[2], const float (&ngv)[16]) {
;     ...
;     const LAS bf16_t* qe0 = (const LAS bf16_t*)(lds + GL_QE0); const LAS bf16_t* qe1 = (const LAS bf16_t*)(lds + GL_QE1); const LAS bf16_t* ke0 = (const LAS bf16_t*)(lds + GL_KE0); const LAS bf16_t* ke1 = (const LAS bf16_t*)(lds + GL_KE1);
;     LAS bf16_t* att = (LAS bf16_t*)(lds + GL_ATT);
;     { const int it = wid >> 1;
; #pragma unroll
;       for (int t2 = 0; t2 < 2; ++t2) { const int jt = (wid & 1) * 2 + t2; f32x4 af = (f32x4){0.f, 0.f, 0.f, 0.f}, ab = af;
;           af = mma_lds(af, qe0 + it * 16 * GLD, ke0 + jt * 16 * GLD, GLD, 2, lane); ab = mma_lds(ab, qe1 + it * 16 * GLD, ke1 + jt * 16 * GLD, GLD, 2, lane);
; #pragma unroll
;           for (int j = 0; j < 4; ++j) { const int i_ = it * 16 + (lane >> 4) * 4 + j, j_ = jt * 16 + (lane & 15); att[i_ * GLD + j_] = f2bf((j_ <= i_ ? af[j] : 0.f) + (j_ >= i_ ? ab[j] : 0.f)); } } }
;     __syncthreads();
;     LAS float* os = (LAS float*)(lds + GL_OS);
;     { const int it = wid >> 1; const LAS bf16_t* sp0 = (const LAS bf16_t*)(lds + GL_SP0); const LAS bf16_t* sp1 = (const LAS bf16_t*)(lds + GL_SP1);
; #pragma unroll
;       for (int t4 = 0; t4 < 4; ++t4) { const int vt = (wid & 1) * 4 + t4; f32x4 acc = (f32x4){0.f, 0.f, 0.f, 0.f};
;           acc = mma_lds_sw(acc, att + it * 16 * GLD, -1, vT + vt * 16 * GLD, vt * 16, GLD, 2, lane); acc = mma_lds(acc, qe0 + it * 16 * GLD, sp0 + vt * 16 * GLD, GLD, 2, lane); acc = mma_lds(acc, qe1 + it * 16 * GLD, sp1 + vt * 16 * GLD, GLD, 2, lane);
; __global__ void __launch_bounds__(512) fwd_megakernel(Params p_in) {
;     ...
;                 { const int head_ = ((b + 128) % G) & 3, kk_ = TID & 63; float wg_[2][16], bg_[2];
;                   _Pragma("unroll") for (int d = 0; d < 2; ++d) { bg_[d] = p.in[16][(l * 2 + d) * 256 + head_ * 64 + kk_]; _Pragma("unroll") for (int j = 0; j < 16; ++j) wg_[d][j] = p.in[15][((size_t)(l * 2 + d) * 16 + j) * 256 + head_ * 64 + kk_]; }
;                   float ng_[16]; _Pragma("unroll") for (int e = 0; e < 16; ++e) ng_[e] = p.in[17][l * 512 + head_ * 128 + (TID & 7) * 16 + e];
;                   for (int it = (b + 128) % G; it < NCK * 4; it += G) gla_item<1>(TID, p, l, it >> 2, it & 3, lds, wg_, bg_, ng_); }
.LBB0_332:
	v_and_b32_e32 v12, 0x70, v146
	s_andn2_b64 vcc, exec, s[2:3]
	s_cbranch_vccnz .LBB0_345
	s_lshl_b32 s1, s0, 7
	s_and_b32 s1, s1, 0x180
	s_or_b32 s1, s1, s20
	v_or_b32_e32 v0, s1, v12
	v_readlane_b32 s40, v254, 32
	v_ashrrev_i32_e32 v1, 31, v0
	v_readlane_b32 s42, v254, 34
	v_readlane_b32 s43, v254, 35
	v_ashrrev_i32_e32 v35, 6, v194
	v_ashrrev_i32_e32 v13, 3, v194
	v_lshl_add_u64 v[18:19], v[0:1], 2, s[42:43]
	global_load_dwordx4 v[0:3], v[18:19], off
	global_load_dwordx4 v[4:7], v[18:19], off offset:16
	global_load_dwordx4 v[8:11], v[18:19], off offset:32
	s_nop 0
	global_load_dwordx4 v[18:21], v[18:19], off offset:48
	v_and_b32_e32 v38, 7, v194
	v_ashrrev_i32_e32 v39, 7, v194
	s_movk_i32 s3, 0x90
	s_movk_i32 s2, 0x900
	v_mul_u32_u24_e32 v31, 0x48, v141
	v_lshlrev_b32_e32 v34, 4, v38
	v_lshlrev_b32_e32 v40, 5, v38
	v_mul_lo_u32 v41, v13, s3
	v_lshlrev_b32_e32 v44, 1, v13
	v_lshlrev_b32_e32 v45, 1, v35
	v_mul_lo_u32 v46, v39, s2
	v_readlane_b32 s9, v253, 44
	v_readlane_b32 s2, v253, 43
	v_lshlrev_b32_e32 v33, 1, v147
	v_bitop3_b32 v42, v35, v194, 7 bitop3:0x78
	v_lshlrev_b32_e32 v48, 1, v31
	v_lshl_or_b32 v40, v13, 8, v40
	v_add3_u32 v84, 0, v41, v34
	v_add3_u32 v85, s9, v41, v34
	v_add3_u32 v86, s2, v41, v34
	v_and_b32_e32 v41, 14, v44
	v_and_b32_e32 v45, 2, v45
	v_lshrrev_b32_e32 v37, 2, v194
	v_mul_u32_u24_e32 v43, 0x480, v38
	v_add3_u32 v50, s9, v33, v48
	v_add_u32_e32 v87, 0, v40
	v_lshl_or_b32 v40, v42, 4, v41
	v_mul_u32_u24_e32 v41, 0x480, v45
	v_readlane_b32 s9, v253, 45
	v_and_b32_e32 v47, 12, v37
	v_add_u32_e32 v49, 0, v46
	v_add3_u32 v90, s9, v43, v40
	v_lshlrev_b32_e32 v40, 1, v41
	v_add3_u32 v52, s2, v33, v48
	v_lshl_or_b32 v39, v39, 4, v47
	v_add3_u32 v89, v49, v48, v33
	v_lshl_or_b32 v42, v45, 4, v141
	v_readlane_b32 s48, v254, 40
	v_readlane_b32 s49, v254, 41
	v_readlane_b32 s50, v254, 42
	v_readlane_b32 s51, v254, 43
	v_readlane_b32 s41, v254, 33
	v_readlane_b32 s44, v254, 36
	v_readlane_b32 s45, v254, 37
	v_readlane_b32 s46, v254, 38
	v_readlane_b32 s47, v254, 39
	v_or_b32_e32 v45, 1, v39
	v_or_b32_e32 v54, 2, v39
	v_readlane_b32 s10, v253, 46
	s_add_i32 s1, 0, 0x20400
	s_add_i32 s8, 0, 0x1bc00
	v_lshlrev_b32_e32 v24, 3, v194
	v_lshl_add_u32 v41, v42, 1, s10
	v_cmp_gt_i32_e64 s[38:39], v42, v39
	v_cmp_lt_i32_e64 s[40:41], v42, v39
	v_cmp_gt_i32_e64 s[42:43], v42, v45
	v_cmp_gt_i32_e64 s[44:45], v42, v54
	v_cmp_lt_i32_e64 s[46:47], v42, v54
	v_add_u32_e32 v36, 0x1000, v24
	v_add_u32_e32 v91, v50, v40
	v_add_u32_e32 v92, v52, v40
	v_bfe_i32 v29, v194, 3, 26
	v_ashrrev_i32_e32 v44, 6, v36
	s_add_u32 s2, s94, 0x12300000
	v_bfe_u32 v80, v194, 4, 2
	v_readlane_b32 s52, v254, 44
	v_readlane_b32 s53, v254, 45
	v_readlane_b32 s54, v254, 46
	v_readlane_b32 s55, v254, 47
	v_lshlrev_b32_e32 v22, 2, v194
	v_mul_lo_u32 v82, v29, s3
	v_mul_lo_u32 v88, v44, s3
	v_mul_lo_u32 v44, v39, s3
	s_addc_u32 s3, s95, 0
	v_lshrrev_b32_e32 v43, 3, v141
	v_bfe_u32 v56, v194, 3, 1
	s_waitcnt vmcnt(3)
	v_mov_b32_e32 v49, v2
	v_add_u32_e32 v2, 0x900, v40
	v_mov_b32_e32 v47, v0
	v_or_b32_e32 v0, 3, v39
	v_add_u32_e32 v93, v50, v2
	v_add_u32_e32 v94, v52, v2
	v_or_b32_e32 v2, 16, v42
	v_cmp_gt_i32_e64 s[48:49], v42, v0
	v_cmp_lt_i32_e64 s[50:51], v42, v0
	v_cmp_gt_i32_e64 s[62:63], v2, v0
	v_cmp_lt_i32_e64 s[64:65], v2, v0
	v_lshlrev_b32_e32 v0, 2, v35
	v_and_b32_e32 v0, 4, v0
	v_mul_u32_u24_e32 v42, 0x480, v0
	s_waitcnt vmcnt(2)
	v_mov_b32_e32 v53, v6
	v_add_u32_e32 v6, s9, v48
	v_add3_u32 v35, s8, v33, v48
	v_add3_u32 v33, s1, v33, v48
	v_lshlrev_b32_e32 v40, 2, v141
	v_lshlrev_b32_e32 v42, 1, v42
	v_lshlrev_b32_e32 v0, 6, v0
	v_cmp_gt_i32_e64 s[56:57], v2, v45
	v_add_u32_e32 v45, v6, v42
	v_add_u32_e32 v95, v35, v42
	v_add_u32_e32 v96, v33, v42
	v_add3_u32 v97, 0, v40, v0
	s_movk_i32 s1, 0x210
	v_add_u32_e32 v0, 0x900, v42
	v_add_u32_e32 v50, 0x1200, v42
	v_add_u32_e32 v42, 0x1b00, v42
	s_waitcnt vmcnt(1)
	v_mov_b32_e32 v55, v8
	s_waitcnt vmcnt(0)
	v_mov_b32_e32 v59, v18
	v_lshrrev_b32_e32 v8, 4, v194
	v_or_b32_e32 v18, 4, v80
	v_mul_lo_u32 v98, v39, s1
	v_add_u32_e32 v99, v35, v0
	v_add_u32_e32 v101, v35, v50
	v_add_u32_e32 v103, v35, v42
	v_mul_lo_u32 v35, v13, s1
	s_ashr_i32 s1, s0, 31
	v_add_u32_e32 v27, 0, v12
	v_add_u32_e32 v26, 0x800, v22
	v_add_u32_e32 v28, 0x1000, v22
	v_add_u32_e32 v30, 0x1800, v22
	v_ashrrev_i32_e32 v25, 31, v24
	v_mov_b32_e32 v51, v4
	v_mov_b32_e32 v61, v20
	v_lshl_add_u32 v4, v2, 1, s10
	v_cmp_gt_i32_e64 s[52:53], v2, v39
	v_cmp_lt_i32_e64 s[54:55], v2, v39
	v_cmp_gt_i32_e64 s[58:59], v2, v54
	v_cmp_lt_i32_e64 s[60:61], v2, v54
	v_add3_u32 v2, s10, v46, v48
	v_lshlrev_b32_e32 v20, 4, v18
	v_bitop3_b32 v8, v43, v8, 3 bitop3:0x78
	v_bitop3_b32 v46, v80, v43, 4 bitop3:0x36
	v_bitop3_b32 v40, v43, v80, 2 bitop3:0x36
	v_bitop3_b32 v48, v43, v18, 2 bitop3:0x36
	v_bitop3_b32 v54, v43, v80, 4 bitop3:0x36
	v_bitop3_b32 v43, v43, v80, 4 bitop3:0x14
	v_bitop3_b32 v58, v56, v80, 6 bitop3:0x36
	v_bitop3_b32 v18, v56, v18, 6 bitop3:0x36
	s_lshl_b64 s[8:9], s[0:1], 15
	v_ashrrev_i32_e32 v23, 31, v22
	v_lshlrev_b32_e32 v32, 3, v38
	v_add_u32_e32 v81, 0x1bc00, v27
	v_add_u32_e32 v83, 0x20400, v27
	v_ashrrev_i32_e32 v27, 31, v26
	v_ashrrev_i32_e32 v29, 31, v28
	v_ashrrev_i32_e32 v31, 31, v30
	v_ashrrev_i32_e32 v37, 31, v36
	v_mov_b32_e32 v57, v10
	v_and_b32_e32 v10, 48, v194
	v_lshlrev_b32_e32 v8, 4, v8
	v_lshlrev_b32_e32 v46, 4, v46
	v_add_u32_e32 v39, v6, v0
	v_lshlrev_b32_e32 v40, 4, v40
	v_lshlrev_b32_e32 v48, 4, v48
	v_add_u32_e32 v100, v33, v0
	v_add_u32_e32 v0, 64, v97
	v_add_u32_e32 v52, v6, v50
	v_lshlrev_b32_e32 v54, 4, v54
	v_lshlrev_b32_e32 v43, 4, v43
	v_add_u32_e32 v102, v33, v50
	v_add_u32_e32 v50, 0x80, v97
	v_add_u32_e32 v6, v6, v42
	v_lshlrev_b32_e32 v58, 4, v58
	v_lshlrev_b32_e32 v18, 4, v18
	v_add_u32_e32 v104, v33, v42
	v_add_u32_e32 v33, 0xc0, v97
	v_lshlrev_b32_e32 v38, 6, v38
	s_add_u32 s28, s94, s8
	v_lshlrev_b64 v[64:65], 1, v[24:25]
	v_mov_b64_e32 v[24:25], 0x4cfc4600
	v_add3_u32 v105, 0, v35, v38
	v_lshlrev_b64 v[62:63], 1, v[36:37]
	s_addc_u32 s29, s95, s9
	v_lshl_add_u64 v[66:67], v[30:31], 2, v[24:25]
	v_lshl_add_u64 v[68:69], v[28:29], 2, v[24:25]
	v_lshl_add_u64 v[70:71], v[26:27], 2, v[24:25]
	v_lshl_add_u64 v[72:73], v[22:23], 2, v[24:25]
	v_lshlrev_b32_e32 v74, 1, v32
	v_lshlrev_b32_e32 v182, 1, v34
	v_add_u32_e32 v106, v41, v44
	v_add_u32_e32 v107, v4, v44
	v_add_u32_e32 v108, v2, v10
	v_add_u32_e32 v109, v45, v8
	v_add_u32_e32 v110, v2, v20
	v_add_u32_e32 v111, v45, v46
	v_add_u32_e32 v112, v39, v40
	v_add_u32_e32 v113, v39, v48
	v_add_u32_e32 v114, v0, v98
	v_add_u32_e32 v115, v52, v54
	v_add_u32_e32 v116, v52, v43
	v_add_u32_e32 v117, v50, v98
	v_add_u32_e32 v118, v6, v58
	v_add_u32_e32 v119, v6, v18
	v_add_u32_e32 v120, v33, v98
	s_mov_b32 s68, 0
	v_readfirstlane_b32 s98, v194
	s_cmpk_gt_u32 s98, 0xff
	s_cbranch_scc0 .Lgla1_noprio
	s_setprio 1

; #define LAS __attribute__((address_space(3)))
; __device__ __forceinline__ float softplus_neg(float lam) { const float e = __expf(-lam); return lam + 0.f < -8.f ? -lam : (e < 0.02f ? e * (1.0f - e * (0.5f - e * (1.0f / 3.0f))) : __logf(1.0f + e)); }
; __device__ __forceinline__ float one_minus_exp(float x) {
;     return x > -0.5f ? -x * (1.0f + x * 0.5f * (1.0f + x * (1.0f / 3.0f) * (1.0f + x * 0.25f * (1.0f + x * 0.2f * (1.0f + x * (1.0f / 6.0f) * (1.0f + x * (1.0f / 7.0f))))))) : 1.0f - __expf(x);
; }
; template <int MODE>
; __device__ __forceinline__ void lru_phase(const int TID, const int b, const int G, const Params& p, int l, LAS unsigned char* lds) {
;     const int tid = TID, lane = tid & 63, wid = tid >> 6, q = lane >> 4;
;     const bf16_t* cols = (const bf16_t*)(p.ws + WS_COLS);
;     int it = b; if (it >= NCK * 8) return;
;     const int nb = b & 7;
;     LAS bf16_t* xcA = (LAS bf16_t*)lds; LAS float* xcf = (LAS float*)(lds + 17408);
;     const int ch = tid & 127, rb = tid >> 7, gchc = nb * 128 + ch;
;     const float w0 = p.in[18][(l * 4 + 0) * 1024 + gchc], w1 = p.in[18][(l * 4 + 1) * 1024 + gchc], w2 = p.in[18][(l * 4 + 2) * 1024 + gchc], w3 = p.in[18][(l * 4 + 3) * 1024 + gchc], cb = p.in[19][l * 1024 + gchc];
;     const int chl = wid * 16 + (lane & 15), gch = nb * 128 + chl;
;     float ba[2], bx[2], sp8[2];
; #pragma unroll
;     for (int d = 0; d < 2; ++d) { ba[d] = p.in[21][(l * 2 + d) * 1024 + gch]; bx[d] = p.in[23][(l * 2 + d) * 1024 + gch]; sp8[d] = 8.0f * softplus_neg(p.in[24][(l * 2 + d) * 1024 + gch]); }
.LBB0_345:
	s_setprio 0
	s_cmpk_gt_i32 s22, 0xc4f
	s_cbranch_scc1 .LBB0_561
	s_lshl_b32 s0, s22, 7
	v_and_b32_e32 v71, 0x7f, v194
	s_and_b32 s28, s0, 0x380
	v_or_b32_e32 v70, s28, v71
	v_readlane_b32 s0, v254, 55
	v_readlane_b32 s40, v254, 32
	v_readlane_b32 s44, v254, 36
	v_or_b32_e32 v0, s0, v70
	v_ashrrev_i32_e32 v1, 31, v0
	v_readlane_b32 s45, v254, 37
	s_movk_i32 s0, 0x2000
	v_readlane_b32 s46, v254, 38
	v_lshl_add_u64 v[0:1], v[0:1], 2, s[44:45]
	v_add_co_u32_e32 v2, vcc, 0x1000, v0
	v_readlane_b32 s47, v254, 39
	s_nop 0
	v_addc_co_u32_e32 v3, vcc, 0, v1, vcc
	v_add_co_u32_e32 v4, vcc, s0, v0
	v_readlane_b32 s0, v254, 57
	s_nop 0
	v_addc_co_u32_e32 v5, vcc, 0, v1, vcc
	v_add_co_u32_e32 v6, vcc, 0x3000, v0
	v_readlane_b32 s41, v254, 33
	s_nop 0
	v_addc_co_u32_e32 v7, vcc, 0, v1, vcc
	global_load_dword v13, v[0:1], off
	global_load_dword v114, v[2:3], off
	global_load_dword v115, v[4:5], off
	global_load_dword v116, v[6:7], off
	v_or_b32_e32 v0, s0, v70
	v_ashrrev_i32_e32 v1, 31, v0
	v_lshl_add_u64 v[0:1], v[0:1], 2, s[46:47]
	global_load_dword v117, v[0:1], off
	v_ashrrev_i32_e32 v0, 2, v194
	v_and_b32_e32 v2, -16, v0
	v_or_b32_e32 v74, v2, v141
	v_add_u32_e32 v72, s28, v74
	v_add_u32_e32 v0, s13, v72
	v_readlane_b32 s42, v254, 34
	v_readlane_b32 s43, v254, 35
	v_ashrrev_i32_e32 v1, 31, v0
	v_readlane_b32 s50, v254, 42
	v_readlane_b32 s51, v254, 43
	v_lshlrev_b64 v[4:5], 2, v[0:1]
	v_readlane_b32 s40, v253, 56
	v_lshl_add_u64 v[6:7], s[50:51], 0, v[4:5]
	v_readlane_b32 s41, v253, 57
	v_readlane_b32 s54, v254, 46
	v_readlane_b32 s55, v254, 47
	global_load_dword v118, v[6:7], off
	v_lshl_add_u64 v[6:7], s[40:41], 0, v[4:5]
	global_load_dword v1, v[6:7], off
	v_lshl_add_u64 v[4:5], s[54:55], 0, v[4:5]
	global_load_dword v119, v[4:5], off
	s_mov_b32 s0, 0xc1000000
	v_readlane_b32 s48, v254, 40
	v_readlane_b32 s49, v254, 41
	v_readlane_b32 s52, v254, 44
	v_readlane_b32 s53, v254, 45
	v_readlane_b32 s42, v253, 58
	v_readlane_b32 s43, v253, 59
	v_readlane_b32 s44, v253, 60
	v_readlane_b32 s45, v253, 61
	v_readlane_b32 s46, v253, 62
	v_readlane_b32 s47, v253, 63
	s_waitcnt vmcnt(0)
	v_xor_b32_e32 v78, 0x80000000, v1
	v_cmp_ngt_f32_e32 vcc, s0, v1
	s_and_saveexec_b64 s[2:3], vcc
	s_cbranch_execz .LBB0_352
	v_mul_f32_e32 v1, 0xbfb8aa3b, v1
	v_exp_f32_e32 v1, v1
	s_mov_b32 s0, 0x3ca3d70a
	v_cmp_ngt_f32_e32 vcc, s0, v1
	s_and_saveexec_b64 s[0:1], vcc
	s_xor_b64 s[38:39], exec, s[0:1]
	s_cbranch_execz .LBB0_349
	v_add_f32_e32 v1, 1.0, v1
	v_cmp_gt_f32_e32 vcc, s19, v1
	s_nop 1
	v_cndmask_b32_e64 v3, 0, 32, vcc
	v_ldexp_f32 v1, v1, v3
	v_log_f32_e32 v1, v1
	s_nop 0
	v_mul_f32_e32 v3, 0x3f317217, v1
	v_fma_f32 v3, v1, s15, -v3
	v_fmac_f32_e32 v3, 0x3377d1cf, v1
	v_fmac_f32_e32 v3, 0x3f317217, v1
	v_cmp_lt_f32_e64 s[0:1], |v1|, s7
	s_nop 1
	v_cndmask_b32_e64 v1, v1, v3, s[0:1]
	v_cndmask_b32_e32 v3, 0, v230, vcc
	v_sub_f32_e32 v78, v1, v3

; __global__ void __launch_bounds__(512) fwd_megakernel(Params p_in) {
;     ...
;                 __syncthreads();
;                 { const int head_ = ((b + 128) % G) & 3, kk_ = TID & 63; float wg_[2][16], bg_[2];
;                   _Pragma("unroll") for (int d = 0; d < 2; ++d) { bg_[d] = p.in[16][(l * 2 + d) * 256 + head_ * 64 + kk_]; _Pragma("unroll") for (int j = 0; j < 16; ++j) wg_[d][j] = p.in[15][((size_t)(l * 2 + d) * 16 + j) * 256 + head_ * 64 + kk_]; }
;                   float ng_[16]; _Pragma("unroll") for (int e = 0; e < 16; ++e) ng_[e] = p.in[17][l * 512 + head_ * 128 + (TID & 7) * 16 + e];
;                   for (int it = (b + 128) % G; it < NCK * 4; it += G) gla_item<0>(TID, p, l, it >> 2, it & 3, lds, wg_, bg_, ng_); }
.LBB0_737:
	s_add_i32 s0, s22, 0x80
	s_ashr_i32 s1, s0, 31
	s_abs_i32 s0, s0
	v_readlane_b32 s2, v253, 38
	s_mul_hi_u32 s2, s0, s2
	v_readlane_b32 s3, v253, 37
	s_mul_i32 s2, s2, s3
	s_sub_i32 s0, s0, s2
	s_sub_i32 s2, s0, s3
	s_cmp_ge_u32 s0, s3
	s_cselect_b32 s0, s2, s0
	s_sub_i32 s2, s0, s3
	s_cmp_ge_u32 s0, s3
	s_cselect_b32 s0, s2, s0
	s_xor_b32 s0, s0, s1
	s_sub_i32 s2, s0, s1
	v_and_b32_e32 v115, 0x7f, v194
	v_and_b32_e32 v112, 63, v194
	s_cmpk_gt_i32 s2, 0x627
	v_ashrrev_i32_e32 v114, 3, v194
	v_lshl_add_u32 v113, v115, 2, 0
	s_waitcnt vmcnt(0) lgkmcnt(0)
	s_barrier
	s_cbranch_scc1 .LBB0_798
	s_lshl_b32 s0, s2, 6
	s_and_b32 s3, s0, 0xc0
	v_readlane_b32 s40, v254, 16
	s_lshl_b32 s0, s3, 2
	v_readlane_b32 s54, v254, 30
	v_readlane_b32 s55, v254, 31
	s_add_u32 s0, s54, s0
	v_readlane_b32 s41, v254, 17
	v_readlane_b32 s42, v254, 18
	v_readlane_b32 s43, v254, 19
	v_readlane_b32 s44, v254, 20
	v_readlane_b32 s45, v254, 21
	v_readlane_b32 s46, v254, 22
	v_readlane_b32 s47, v254, 23
	v_readlane_b32 s48, v254, 24
	v_readlane_b32 s49, v254, 25
	v_readlane_b32 s50, v254, 26
	v_readlane_b32 s51, v254, 27
	v_readlane_b32 s52, v254, 28
	v_readlane_b32 s53, v254, 29
	s_addc_u32 s1, s55, 0
	v_lshlrev_b32_e32 v182, 2, v112
	v_or_b32_e32 v2, s20, v112
	v_lshl_add_u64 v[0:1], s[0:1], 0, v[182:183]
	v_or_b32_e32 v2, s3, v2
	v_readlane_b32 s40, v254, 32
	v_readlane_b32 s0, v254, 61
	v_ashrrev_i32_e32 v3, 31, v2
	v_readlane_b32 s41, v254, 33
	v_readlane_b32 s1, v254, 62
	s_mov_b32 s10, s0
	s_ashr_i32 s11, s0, 31
	v_lshl_add_u64 v[2:3], v[2:3], 2, s[40:41]
	s_lshl_b64 s[0:1], s[10:11], 14
	global_load_dword v116, v[2:3], off
	v_lshl_add_u64 v[2:3], v[0:1], 0, s[0:1]
	s_mov_b32 s0, s10
	v_readlane_b32 s42, v254, 34
	v_readlane_b32 s43, v254, 35
	v_readlane_b32 s44, v254, 36
	v_readlane_b32 s45, v254, 37
	v_readlane_b32 s46, v254, 38
	v_readlane_b32 s47, v254, 39
	v_readlane_b32 s48, v254, 40
	v_readlane_b32 s49, v254, 41
	v_readlane_b32 s50, v254, 42
	v_readlane_b32 s51, v254, 43
	v_readlane_b32 s52, v254, 44
	v_readlane_b32 s53, v254, 45
	v_readlane_b32 s54, v254, 46
	v_readlane_b32 s55, v254, 47
	s_movk_i32 s9, 0x1000
	v_writelane_b32 v254, s0, 61
	v_add_co_u32_e32 v4, vcc, s9, v2
	s_nop 0
	v_writelane_b32 v254, s1, 62
	s_or_b32 s0, s10, 1
	v_addc_co_u32_e32 v5, vcc, 0, v3, vcc
	global_load_dword v117, v[2:3], off
	global_load_dword v118, v[2:3], off offset:1024
	global_load_dword v119, v[2:3], off offset:2048
	global_load_dword v120, v[2:3], off offset:3072
	global_load_dword v121, v[4:5], off offset:1024
	global_load_dword v30, v[4:5], off offset:2048
	global_load_dword v31, v[4:5], off offset:3072
	v_lshl_or_b32 v4, s0, 8, v112
	s_movk_i32 s8, 0x2000
	v_or_b32_e32 v4, s3, v4
	s_ashr_i32 s1, s0, 31
	v_add_co_u32_e32 v6, vcc, s8, v2
	v_ashrrev_i32_e32 v5, 31, v4
	s_lshl_b64 s[0:1], s[0:1], 14
	v_addc_co_u32_e32 v7, vcc, 0, v3, vcc
	v_lshl_add_u64 v[4:5], v[4:5], 2, s[40:41]
	v_lshl_add_u64 v[0:1], v[0:1], 0, s[0:1]
	global_load_dword v122, v[4:5], off
	v_add_co_u32_e32 v4, vcc, s9, v0
	s_movk_i32 s0, 0x3000
	s_nop 0
	v_addc_co_u32_e32 v5, vcc, 0, v1, vcc
	v_add_co_u32_e32 v8, vcc, s8, v0
	v_ashrrev_i32_e32 v50, 6, v194
	s_nop 0
	v_addc_co_u32_e32 v9, vcc, 0, v1, vcc
	v_add_co_u32_e32 v10, vcc, s0, v0
	s_add_u32 s28, s94, 0x12300000
	s_nop 0
	v_addc_co_u32_e32 v11, vcc, 0, v1, vcc
	v_add_co_u32_e32 v2, vcc, s0, v2
	v_bitop3_b32 v12, v50, v194, 7 bitop3:0x78
	s_nop 0
	v_addc_co_u32_e32 v3, vcc, 0, v3, vcc
	global_load_dword v123, v[6:7], off offset:-4096
	global_load_dword v33, v[10:11], off offset:3072
	global_load_dword v35, v[2:3], off offset:3072
	global_load_dword v34, v[2:3], off offset:2048
	global_load_dword v37, v[2:3], off offset:1024
	global_load_dword v36, v[2:3], off
	global_load_dword v32, v[10:11], off offset:2048
	global_load_dword v39, v[10:11], off offset:1024
	global_load_dword v124, v[0:1], off
	global_load_dword v125, v[0:1], off offset:1024
	global_load_dword v126, v[0:1], off offset:2048
	global_load_dword v127, v[0:1], off offset:3072
	global_load_dword v128, v[4:5], off offset:1024
	global_load_dword v40, v[4:5], off offset:2048
	global_load_dword v41, v[4:5], off offset:3072
	global_load_dword v38, v[10:11], off
	global_load_dword v43, v[8:9], off offset:3072
	global_load_dword v129, v[8:9], off offset:-4096
	global_load_dword v42, v[8:9], off offset:2048
	global_load_dword v45, v[8:9], off offset:1024
	global_load_dword v44, v[8:9], off
	global_load_dword v47, v[6:7], off offset:3072
	global_load_dword v46, v[6:7], off offset:2048
	global_load_dword v49, v[6:7], off offset:1024
	global_load_dword v48, v[6:7], off
	v_and_b32_e32 v1, 7, v194
	v_and_b32_e32 v13, 7, v114
	s_addc_u32 s29, s95, 0
	s_add_i32 s0, 0, 0x4000
	v_lshl_or_b32 v12, v12, 3, v13
	v_lshlrev_b32_e32 v13, 5, v1
	v_lshlrev_b32_e32 v27, 8, v114
	v_mov_b32_e32 v7, s0
	v_add_u32_e32 v151, 0, v13
	v_or_b32_e32 v13, v27, v13
	s_movk_i32 s0, 0x240
	v_lshlrev_b32_e32 v0, 3, v1
	v_add_u32_e32 v152, 0, v13
	v_mad_u32_u24 v13, v1, s0, v12
	v_lshl_add_u32 v153, v13, 1, 0
	v_or_b32_e32 v13, 1, v0
	s_movk_i32 s0, 0x48
	v_or_b32_e32 v3, 64, v0
	v_lshlrev_b32_e32 v2, 2, v1
	v_lshlrev_b32_e32 v5, 4, v1
	v_mad_u32_u24 v13, v13, s0, v12
	v_mul_u32_u24_e32 v1, 0x480, v1
	v_lshlrev_b32_e32 v12, 1, v12
	v_readlane_b32 s3, v253, 45
	v_ashrrev_i32_e32 v51, 31, v50
	v_lshl_add_u32 v155, v13, 1, 0
	v_add3_u32 v162, s3, v1, v12
	v_mul_u32_u24_e32 v1, 0x90, v3
	v_add3_u32 v163, s3, v1, v12
	v_lshlrev_b64 v[12:13], 8, v[50:51]
	v_lshrrev_b32_e32 v28, 4, v112
	v_lshrrev_b32_e32 v51, 3, v142
	v_xor_b32_e32 v52, v51, v28
	v_bitop3_b32 v51, v28, v51, 4 bitop3:0x36
	v_lshlrev_b32_e32 v4, 7, v114
; template <int MODE>
; __device__ __forceinline__ void gla_item(const int TID, const Params& p, int l, int ci, int head, LAS unsigned char* lds, const float (&wg)[2][16], const float (&bg)[2], const float (&ngv)[16]) {
;     ...
;       if (MODE == 0) { LAS bf16_t* kd0 = (LAS bf16_t*)(lds + GL_QE0); LAS bf16_t* kd1 = (LAS bf16_t*)(lds + GL_QE1);
; #pragma unroll
;           for (int i = 0; i < 8; ++i) { const int kk = k8 + i; kd0[kk * GLD + SWZ(kk, r)] = f2bf(kv[i] * __expf(bfs[63 * 64 + kk] - bfs[r * 64 + kk])); kd1[kk * GLD + SWZ(kk, r)] = f2bf(kv[i] * __expf(bbs[kk] - bbs[r * 64 + kk])); }
;       } else { LAS bf16_t* qe0 = (LAS bf16_t*)(lds + GL_QE0); LAS bf16_t* qe1 = (LAS bf16_t*)(lds + GL_QE1); LAS bf16_t* ke0 = (LAS bf16_t*)(lds + GL_KE0); LAS bf16_t* ke1 = (LAS bf16_t*)(lds + GL_KE1);
;           u32x4 a, b2, c2, d2;
; #pragma unroll
;           for (int i = 0; i < 4; ++i) { const int kk = k8 + 2 * i; const float f0 = bfs[r * 64 + kk], f1 = bfs[r * 64 + kk + 1], g0 = bbs[r * 64 + kk], g1 = bbs[r * 64 + kk + 1];
;               a[i] = cvt_pk_bf16(qv[2 * i] * 0.125f * __expf(f0), qv[2 * i + 1] * 0.125f * __expf(f1)); b2[i] = cvt_pk_bf16(qv[2 * i] * 0.125f * __expf(g0), qv[2 * i + 1] * 0.125f * __expf(g1));
;               c2[i] = cvt_pk_bf16(kv[2 * i] * __expf(-f0), kv[2 * i + 1] * __expf(-f1)); d2[i] = cvt_pk_bf16(kv[2 * i] * __expf(-g0), kv[2 * i + 1] * __expf(-g1)); }
;           *(LAS u32x4*)(qe0 + r * GLD + k8) = a; *(LAS u32x4*)(qe1 + r * GLD + k8) = b2; *(LAS u32x4*)(ke0 + r * GLD + k8) = c2; *(LAS u32x4*)(ke1 + r * GLD + k8) = d2; }
; #pragma unroll
;       for (int hh = 0; hh < 2; ++hh) { const int v8 = ((tid & 7) + 8 * hh) * 8; u32x4 vw = (u32x4){0u, 0u, 0u, 0u};
;           if (ok) vw = vwp[hh];
; #pragma unroll
;           for (int i = 0; i < 4; ++i) { vT[(v8 + 2 * i) * GLD + SWZ(v8, r)] = (bf16_t)(vw[i] & 0xffffu); vT[(v8 + 2 * i + 1) * GLD + SWZ(v8, r)] = (bf16_t)(vw[i] >> 16); } }
;     }
;     if (MODE == 1) {
;         const bf16_t* spb = (const bf16_t*)(p.ws + WS_SPB); u32x4 sv[2][2];
; #pragma unroll
;         for (int d = 0; d < 2; ++d) { const bf16_t* src = spb + ((size_t)(ci * 4 + head) * 2 + d) * 8192;
; #pragma unroll
;             for (int i = 0; i < 2; ++i) sv[d][i] = *(const u32x4*)(src + (i * 512 + tid) * 8); }
; #pragma unroll
;         for (int d = 0; d < 2; ++d) { LAS bf16_t* sp = (LAS bf16_t*)(lds + (d ? GL_SP1 : GL_SP0));
	v_lshlrev_b32_e32 v98, 4, v51
	v_or_b32_e32 v51, 16, v142
	v_add3_u32 v130, 0, v4, v5
	v_lshlrev_b32_e32 v4, 2, v194
	s_add_i32 s1, 0, 0x8000
	v_lshrrev_b32_e32 v51, 3, v51
	v_add_u32_e32 v131, 0, v4
	v_add_u32_e32 v132, 8, v50
	v_mov_b32_e32 v6, s1
	v_cmp_gt_u32_e32 vcc, 64, v115
	s_movk_i32 s0, 0x80
	v_lshlrev_b32_e32 v97, 4, v52
	v_xor_b32_e32 v52, v51, v28
	v_bitop3_b32 v51, v51, v28, 4 bitop3:0x1e
	v_lshl_or_b32 v5, v132, 8, v182
	v_add_u32_e32 v135, 16, v50
	v_cndmask_b32_e32 v6, v6, v7, vcc
	v_add_u32_e32 v154, v151, v27
	v_cmp_gt_i32_e64 s[56:57], s0, v194
	v_add_u32_e32 v1, 0x7f00, v131
	v_add_u32_e32 v3, s1, v182
	v_cmp_gt_u32_e32 vcc, 64, v194
	s_movk_i32 s0, 0x900
	v_mul_u32_u24_e32 v27, 0x48, v142
	v_lshlrev_b32_e32 v100, 4, v51
	v_or_b32_e32 v51, 32, v142
	v_add_u32_e32 v133, 0, v5
	v_lshl_or_b32 v5, v135, 8, v182
	v_add_u32_e32 v137, 24, v50
	v_cndmask_b32_e32 v164, v3, v1, vcc
	v_mul_lo_u32 v1, v50, s0
	v_lshlrev_b32_e32 v27, 1, v27
	v_lshrrev_b32_e32 v51, 3, v51
	v_add_u32_e32 v136, 0, v5
	v_lshl_or_b32 v5, v137, 8, v182
	v_add_u32_e32 v139, 32, v50
	v_add3_u32 v1, s3, v1, v27
	v_lshlrev_b32_e32 v99, 4, v52
	v_xor_b32_e32 v52, v51, v28
	v_bitop3_b32 v51, v51, v28, 4 bitop3:0x1e
	s_ashr_i32 s3, s2, 31
	v_add_u32_e32 v138, 0, v5
	v_lshl_or_b32 v5, v139, 8, v182
	v_add_u32_e32 v141, 40, v50
	v_lshlrev_b32_e32 v102, 4, v51
	v_or_b32_e32 v51, 48, v142
	s_lshl_b64 s[0:1], s[2:3], 9
	v_add_u32_e32 v140, 0, v5
	v_lshl_or_b32 v5, v141, 8, v182
	v_add_u32_e32 v145, 48, v50
	v_lshrrev_b32_e32 v51, 3, v51
	s_add_u32 s0, s0, 0x47820000
	v_add_u32_e32 v144, 0, v5
	v_lshl_or_b32 v5, v145, 8, v182
	v_add_u32_e32 v147, 56, v50
	v_lshlrev_b32_e32 v101, 4, v52
	v_xor_b32_e32 v52, v51, v28
	s_addc_u32 s1, s1, 0
	v_add_u32_e32 v146, 0, v5
	v_lshl_or_b32 v5, v147, 8, v182
	v_lshlrev_b32_e32 v103, 4, v52
	v_lshl_add_u64 v[52:53], s[0:1], 0, v[12:13]
	s_lshl_b64 s[0:1], s[2:3], 15
	v_add_u32_e32 v148, 0, v5
	v_ashrrev_i32_e32 v5, 7, v194
	s_add_u32 s58, s0, 0x4cfc4600
	v_lshlrev_b32_e32 v7, 12, v5
	v_cmp_gt_i32_e64 s[40:41], 0, v5
	v_cmp_lt_i32_e64 s[42:43], 0, v5
	v_cmp_gt_i32_e64 s[44:45], 1, v5
	v_cmp_lt_i32_e64 s[46:47], 1, v5
	v_cmp_gt_i32_e64 s[48:49], 2, v5
	v_cmp_lt_i32_e64 s[50:51], 2, v5
	v_cmp_gt_i32_e64 s[52:53], 3, v5
	v_cmp_lt_i32_e64 s[54:55], 3, v5
	v_lshlrev_b32_e32 v26, 4, v194
	v_ashrrev_i32_e32 v5, 31, v4
	s_addc_u32 s59, s1, 0
	v_add3_u32 v149, v6, v7, v182
	v_add_u32_e32 v6, 0x800, v4
	v_add_u32_e32 v8, 0x1000, v4
	v_add_u32_e32 v10, 0x1800, v4
	v_lshl_add_u64 v[54:55], v[4:5], 2, s[58:59]
	v_and_b32_e32 v4, 0x300, v26
	v_lshl_or_b32 v4, v50, 10, v4
	v_ashrrev_i32_e32 v5, 31, v4
	v_or_b32_e32 v4, v4, v142
	v_ashrrev_i32_e32 v7, 31, v6
	v_lshl_add_u64 v[56:57], v[4:5], 1, s[0:1]
	v_ashrrev_i32_e32 v5, 31, v4
	v_lshl_add_u64 v[58:59], v[6:7], 2, s[58:59]
	v_lshl_add_u64 v[64:65], v[4:5], 1, s[0:1]
	s_add_u32 s0, s0, 0x415a4000
	v_or_b32_e32 v6, 0xf0, v4
	s_addc_u32 s1, s1, 0
	v_ashrrev_i32_e32 v7, 31, v6
	v_lshl_add_u64 v[66:67], v[6:7], 1, s[0:1]
	v_or_b32_e32 v6, 0xb0, v4
	v_ashrrev_i32_e32 v7, 31, v6
	v_lshl_add_u64 v[68:69], v[6:7], 1, s[0:1]
	v_or_b32_e32 v6, 0x70, v4
	v_ashrrev_i32_e32 v7, 31, v6
	v_lshl_add_u64 v[70:71], v[6:7], 1, s[0:1]
	v_or_b32_e32 v6, 48, v4
	v_ashrrev_i32_e32 v7, 31, v6
	v_lshl_add_u64 v[72:73], v[6:7], 1, s[0:1]
	v_or_b32_e32 v6, 0xe0, v4
	v_ashrrev_i32_e32 v7, 31, v6
	v_lshl_add_u64 v[74:75], v[6:7], 1, s[0:1]
	v_or_b32_e32 v6, 0xa0, v4
	v_ashrrev_i32_e32 v7, 31, v6
	v_lshl_add_u64 v[76:77], v[6:7], 1, s[0:1]
	v_or_b32_e32 v6, 0x60, v4
	v_ashrrev_i32_e32 v7, 31, v6
	v_lshl_add_u64 v[78:79], v[6:7], 1, s[0:1]
	v_or_b32_e32 v6, 32, v4
	v_ashrrev_i32_e32 v7, 31, v6
	v_lshl_add_u64 v[80:81], v[6:7], 1, s[0:1]
	v_or_b32_e32 v6, 0xd0, v4
	v_ashrrev_i32_e32 v7, 31, v6
	v_lshl_add_u64 v[82:83], v[6:7], 1, s[0:1]
	v_or_b32_e32 v6, 0x90, v4
	v_ashrrev_i32_e32 v7, 31, v6
	v_lshl_add_u64 v[84:85], v[6:7], 1, s[0:1]
	v_or_b32_e32 v6, 0x50, v4
	v_ashrrev_i32_e32 v7, 31, v6
	v_lshl_add_u64 v[86:87], v[6:7], 1, s[0:1]
	v_or_b32_e32 v6, 16, v4
	v_lshl_or_b32 v3, v50, 4, v142
	v_ashrrev_i32_e32 v7, 31, v6
	v_bfe_u32 v3, v3, 3, 3
	v_cmp_lt_i32_e32 vcc, -1, v50
	v_lshl_add_u64 v[88:89], v[6:7], 1, s[0:1]
	v_or_b32_e32 v6, 0xc0, v4
	v_cndmask_b32_e32 v3, 0, v3, vcc
	v_ashrrev_i32_e32 v7, 31, v6
	v_xor_b32_e32 v29, v3, v28
	v_bitop3_b32 v3, v3, v28, 4 bitop3:0x1e
	v_bitop3_b32 v28, v51, v28, 4 bitop3:0x1e
	v_lshl_add_u64 v[90:91], v[6:7], 1, s[0:1]
	v_or_b32_e32 v6, 0x80, v4
	v_or_b32_e32 v4, 64, v4
	v_lshlrev_b32_e32 v18, 7, v50
	v_lshlrev_b32_e32 v19, 7, v132
	v_lshlrev_b32_e32 v20, 7, v135
	v_lshlrev_b32_e32 v21, 7, v137
	v_lshlrev_b32_e32 v22, 7, v139
	v_lshlrev_b32_e32 v23, 7, v141
	v_lshlrev_b32_e32 v24, 7, v145
	v_lshlrev_b32_e32 v25, 7, v147
	v_ashrrev_i32_e32 v9, 31, v8
	v_ashrrev_i32_e32 v11, 31, v10
	v_add_u32_e32 v27, 0, v27
	v_lshlrev_b32_e32 v29, 4, v29
	v_lshlrev_b32_e32 v3, 4, v3
	v_lshlrev_b32_e32 v28, 4, v28
	v_ashrrev_i32_e32 v7, 31, v6
	v_ashrrev_i32_e32 v5, 31, v4
	v_cmp_lt_u32_e64 s[38:39], 63, v115
	v_add_u32_e32 v150, 0, v26
	v_add_u32_e32 v156, 0x90, v155
	v_add_u32_e32 v157, 0x120, v155
	v_add_u32_e32 v158, 0x1b0, v155
	v_add_u32_e32 v159, 0x240, v155
	v_add_u32_e32 v160, 0x2d0, v155
	v_add_u32_e32 v161, 0x360, v155
	v_or_b32_e32 v52, v52, v182
	v_lshl_add_u64 v[60:61], v[8:9], 2, s[58:59]
	v_lshl_add_u64 v[62:63], v[10:11], 2, s[58:59]
	v_lshl_add_u64 v[92:93], v[6:7], 1, s[0:1]
	v_lshl_add_u64 v[94:95], v[4:5], 1, s[0:1]
	v_lshlrev_b32_e32 v182, 1, v0
	v_lshlrev_b32_e32 v96, 1, v2
	v_add_u32_e32 v51, 0, v18
	v_add_u32_e32 v165, 0, v19
	v_add_u32_e32 v166, 0, v20
	v_add_u32_e32 v167, 0, v21
	v_add_u32_e32 v168, 0, v22
	v_add_u32_e32 v169, 0, v23
	v_add_u32_e32 v170, 0, v24
	v_add_u32_e32 v171, 0, v25
	v_add_u32_e32 v172, v1, v29
	v_add_u32_e32 v173, v27, v97
	v_add_u32_e32 v174, v1, v3
	v_add_u32_e32 v175, v27, v98
	v_add_u32_e32 v176, v27, v99
	v_add_u32_e32 v177, v27, v100
	v_add_u32_e32 v178, v27, v101
	v_add_u32_e32 v179, v27, v102
	v_add_u32_e32 v180, v27, v103
	v_add_u32_e32 v181, v27, v28
	s_mov_b32 s62, 0
	v_readfirstlane_b32 s98, v194
	s_cmpk_gt_u32 s98, 0xff
	s_cbranch_scc0 .Lgla0_noprio
	s_setprio 1

; #define LAS __attribute__((address_space(3)))
; __device__ __forceinline__ float softplus_neg(float lam) { const float e = __expf(-lam); return lam + 0.f < -8.f ? -lam : (e < 0.02f ? e * (1.0f - e * (0.5f - e * (1.0f / 3.0f))) : __logf(1.0f + e)); }
; __device__ __forceinline__ float one_minus_exp(float x) {
;     return x > -0.5f ? -x * (1.0f + x * 0.5f * (1.0f + x * (1.0f / 3.0f) * (1.0f + x * 0.25f * (1.0f + x * 0.2f * (1.0f + x * (1.0f / 6.0f) * (1.0f + x * (1.0f / 7.0f))))))) : 1.0f - __expf(x);
; }
; template <int MODE>
; __device__ __forceinline__ void lru_phase(const int TID, const int b, const int G, const Params& p, int l, LAS unsigned char* lds) {
;     const int tid = TID, lane = tid & 63, wid = tid >> 6, q = lane >> 4;
;     const bf16_t* cols = (const bf16_t*)(p.ws + WS_COLS);
;     int it = b; if (it >= NCK * 8) return;
;     const int nb = b & 7;
;     LAS bf16_t* xcA = (LAS bf16_t*)lds; LAS float* xcf = (LAS float*)(lds + 17408);
;     const int ch = tid & 127, rb = tid >> 7, gchc = nb * 128 + ch;
;     const float w0 = p.in[18][(l * 4 + 0) * 1024 + gchc], w1 = p.in[18][(l * 4 + 1) * 1024 + gchc], w2 = p.in[18][(l * 4 + 2) * 1024 + gchc], w3 = p.in[18][(l * 4 + 3) * 1024 + gchc], cb = p.in[19][l * 1024 + gchc];
;     const int chl = wid * 16 + (lane & 15), gch = nb * 128 + chl;
;     float ba[2], bx[2], sp8[2];
; #pragma unroll
;     for (int d = 0; d < 2; ++d) { ba[d] = p.in[21][(l * 2 + d) * 1024 + gch]; bx[d] = p.in[23][(l * 2 + d) * 1024 + gch]; sp8[d] = 8.0f * softplus_neg(p.in[24][(l * 2 + d) * 1024 + gch]); }
.LBB0_798:
	s_setprio 0
	s_cmpk_gt_i32 s22, 0xc4f
	s_cbranch_scc1 .LBB0_1012
	s_lshl_b32 s0, s22, 7
	s_and_b32 s24, s0, 0x380
	v_or_b32_e32 v70, s24, v115
	v_readlane_b32 s0, v254, 55
	v_readlane_b32 s40, v254, 32
	v_readlane_b32 s44, v254, 36
	v_or_b32_e32 v0, s0, v70
	v_ashrrev_i32_e32 v1, 31, v0
	v_readlane_b32 s45, v254, 37
	v_readlane_b32 s0, v254, 57
	v_readlane_b32 s46, v254, 38
	v_lshl_add_u64 v[0:1], v[0:1], 2, s[44:45]
	v_add_co_u32_e32 v2, vcc, 0x1000, v0
	v_readlane_b32 s47, v254, 39
	s_nop 0
	v_addc_co_u32_e32 v3, vcc, 0, v1, vcc
	v_add_co_u32_e32 v4, vcc, 0x2000, v0
	v_readlane_b32 s41, v254, 33
	s_nop 0
	v_addc_co_u32_e32 v5, vcc, 0, v1, vcc
	v_add_co_u32_e32 v6, vcc, 0x3000, v0
	v_readlane_b32 s42, v254, 34
	s_nop 0
	v_addc_co_u32_e32 v7, vcc, 0, v1, vcc
	global_load_dword v104, v[0:1], off
	global_load_dword v105, v[2:3], off
	global_load_dword v106, v[4:5], off
	global_load_dword v107, v[6:7], off
	v_or_b32_e32 v0, s0, v70
	v_ashrrev_i32_e32 v1, 31, v0
	v_lshl_add_u64 v[0:1], v[0:1], 2, s[46:47]
	global_load_dword v108, v[0:1], off
	v_ashrrev_i32_e32 v0, 2, v194
	v_and_b32_e32 v2, -16, v0
	v_or_b32_e32 v72, v2, v142
	v_add_u32_e32 v12, s24, v72
	v_add_u32_e32 v0, s13, v12
	v_readlane_b32 s43, v254, 35
	v_ashrrev_i32_e32 v1, 31, v0
	v_readlane_b32 s50, v254, 42
	v_readlane_b32 s51, v254, 43
	v_lshlrev_b64 v[4:5], 2, v[0:1]
	v_readlane_b32 s40, v253, 56
	v_lshl_add_u64 v[6:7], s[50:51], 0, v[4:5]
	v_readlane_b32 s41, v253, 57
	v_readlane_b32 s54, v254, 46
	v_readlane_b32 s55, v254, 47
	global_load_dword v109, v[6:7], off
	v_lshl_add_u64 v[6:7], s[40:41], 0, v[4:5]
	global_load_dword v1, v[6:7], off
	v_lshl_add_u64 v[4:5], s[54:55], 0, v[4:5]
	global_load_dword v110, v[4:5], off
	s_mov_b32 s0, 0xc1000000
	v_readlane_b32 s48, v254, 40
	v_readlane_b32 s49, v254, 41
	v_readlane_b32 s52, v254, 44
	v_readlane_b32 s53, v254, 45
	v_readlane_b32 s42, v253, 58
	v_readlane_b32 s43, v253, 59
	v_readlane_b32 s44, v253, 60
	v_readlane_b32 s45, v253, 61
	v_readlane_b32 s46, v253, 62
	v_readlane_b32 s47, v253, 63
	s_waitcnt vmcnt(0)
	v_xor_b32_e32 v71, 0x80000000, v1
	v_cmp_ngt_f32_e32 vcc, s0, v1
	s_and_saveexec_b64 s[2:3], vcc
	s_cbranch_execz .LBB0_805
	v_mul_f32_e32 v1, 0xbfb8aa3b, v1
	v_exp_f32_e32 v1, v1
	s_mov_b32 s0, 0x3ca3d70a
	v_cmp_ngt_f32_e32 vcc, s0, v1
	s_and_saveexec_b64 s[0:1], vcc
	s_xor_b64 s[28:29], exec, s[0:1]
	s_cbranch_execz .LBB0_802
	v_add_f32_e32 v1, 1.0, v1
	v_cmp_gt_f32_e32 vcc, s19, v1
	s_nop 1
	v_cndmask_b32_e64 v3, 0, 32, vcc
	v_ldexp_f32 v1, v1, v3
	v_log_f32_e32 v1, v1
	s_nop 0
	v_mul_f32_e32 v3, 0x3f317217, v1
	v_fma_f32 v3, v1, s15, -v3
	v_fmac_f32_e32 v3, 0x3377d1cf, v1
	v_fmac_f32_e32 v3, 0x3f317217, v1
	v_cmp_lt_f32_e64 s[0:1], |v1|, s7
	s_nop 1
	v_cndmask_b32_e64 v1, v1, v3, s[0:1]
	v_cndmask_b32_e32 v3, 0, v230, vcc
	v_sub_f32_e32 v71, v1, v3
